# skip the empty context-LayerNorm phase 12 of the last layer: one grid barrier instead of two between w_out GEMM and ffn_in GEMM
# speedup vs baseline: 1.0000x; 1.0000x over previous
.LBB0_1378:
	s_add_i32 s54, s54, 1
	s_cmp_eq_u32 s54, 12
	s_cselect_b32 s54, 13, s54
	s_cmp_eq_u32 s54, 15
	s_cselect_b32 s54, s55, s54
	v_readlane_b32 s26, v254, 21
	v_readlane_b32 s36, v254, 25
	v_readlane_b32 s40, v254, 29
	s_cmp_ge_i32 s54, s55
	v_readlane_b32 s27, v254, 22
	v_readlane_b32 s37, v254, 26
	v_readlane_b32 s41, v254, 30
	s_cbranch_scc1 .Lskip_seam
	s_cmp_eq_u32 s54, 6
	s_cbranch_scc1 .Lskip_seam
	s_cmp_eq_u32 s54, 9
	s_cbranch_scc0 .LBB0_1379
